# per-layer norm loop: norm weight loaded once per phase, each row's modulation scale/shift chunks loaded in one batch (was a load->wait round trip per 256-column chunk that also drained the previous ch
# speedup vs baseline: 1.0110x; 1.0071x over previous
; DI int ltid_w(int wave) { int t; asm volatile("v_mbcnt_lo_u32_b32 %0, -1, 0\n\tv_mbcnt_hi_u32_b32 %0, -1, %0" : "=v"(t)); return (wave << 6) | t; }
; DI void ph_norm(const Params& p, int l, int bid, int nb) {
;   const int tid_ = ltid_w(p.wave); const int lane = tid_ & 63, w = tid_ >> 6;
;   bf16_t* H = (bf16_t*)(p.ws + WS_HM);
;   const float* MOD = (const float*)(p.ws + WS_MOD);
;   const float* g = p.norm_g + l * DM;
;   for (int it = bid; it < ROWS / 8; it += nb) {
;     float4 v[2][4];
;     const float* mod[2];
; #pragma unroll
;     for (int rr = 0; rr < 2; ++rr) {
;       const int row = it * 8 + rr * 4 + w;
;       const int b = row / NTOK, t = row % NTOK;
;       const float* src = xsrc_row(p, l, b, t);
;       mod[rr] = MOD + ((size_t)l * 9 + (t < NCTX ? 8 : b)) * 3072;
; #pragma unroll
;       for (int i = 0; i < 4; ++i) v[rr][i] = *(const float4*)(src + (i * 64 + lane) * 4);
;     }
; #pragma unroll
;     for (int rr = 0; rr < 2; ++rr) {
;       const int row = it * 8 + rr * 4 + w;
;       float ss = 0.f;
; #pragma unroll
;       for (int i = 0; i < 4; ++i) ss += v[rr][i].x * v[rr][i].x + v[rr][i].y * v[rr][i].y + v[rr][i].z * v[rr][i].z + v[rr][i].w * v[rr][i].w;
;       ss = wave_sum(ss);
;       const float rstd = rsqrtf(ss * (1.f / DM) + EPS);
; #pragma unroll
;       for (int i = 0; i < 4; ++i) {
;         const int j = (i * 64 + lane) * 4;
;         const float4 gg = *(const float4*)(g + j);
;         const float4 sh = *(const float4*)(mod[rr] + j);
;         const float4 sc = *(const float4*)(mod[rr] + 1024 + j);
.LBB0_112:
	v_writelane_b32 v254, s72, 15
	s_andn2_b64 vcc, exec, s[0:1]
	s_mov_b32 s0, s48
	v_writelane_b32 v254, s73, 16
	v_writelane_b32 v254, s0, 17
	s_nop 1
	v_writelane_b32 v254, s1, 18
	s_cbranch_vccnz .LBB0_156
	v_readlane_b32 s0, v253, 59
	v_readlane_b32 s1, v253, 60
	s_andn2_b64 vcc, exec, s[0:1]
	v_mbcnt_lo_u32_b32 v0, -1, 0
	v_mbcnt_hi_u32_b32 v0, -1, v0
	s_cbranch_vccnz .LBB0_124
	v_readlane_b32 s0, v253, 0
	v_cmp_lt_i32_e32 vcc, v184, v178
	v_readlane_b32 s72, v253, 7
	v_or_b32_e32 v1, s0, v0
	v_ashrrev_i32_e32 v3, 6, v1
	v_cndmask_b32_e32 v1, v177, v184, vcc
	v_cmp_lt_i32_e32 vcc, v183, v178
	s_waitcnt vmcnt(0)
	v_lshlrev_b32_e32 v60, 2, v1
	s_add_u32 s0, s68, 0x1580000
	v_cndmask_b32_e32 v1, v177, v183, vcc
	v_cmp_lt_i32_e32 vcc, v182, v178
	v_lshlrev_b32_e32 v61, 2, v1
	s_addc_u32 s1, s69, 0
	v_cndmask_b32_e32 v1, v177, v182, vcc
	v_cmp_lt_i32_e32 vcc, v181, v178
	s_lshl_b32 s2, s48, 10
	v_readlane_b32 s84, v253, 19
	v_readlane_b32 s85, v253, 20
	v_lshlrev_b32_e32 v62, 2, v1
	v_cndmask_b32_e32 v1, v177, v181, vcc
	v_cmp_lt_i32_e32 vcc, v180, v178
	s_lshl_b64 s[4:5], s[2:3], 2
	v_readlane_b32 s86, v253, 21
	v_readlane_b32 s87, v253, 22
	s_mov_b64 s[20:21], s[84:85]
	v_lshlrev_b32_e32 v5, 2, v0
	v_lshlrev_b32_e32 v63, 2, v1
	v_cndmask_b32_e32 v1, v177, v180, vcc
	v_cmp_lt_i32_e32 vcc, v179, v178
	v_lshlrev_b32_e32 v0, 3, v0
	s_add_u32 s4, s20, s4
	v_lshlrev_b32_e32 v64, 2, v1
	v_cndmask_b32_e32 v1, v177, v179, vcc
	v_and_b32_e32 v160, 56, v0
	v_readlane_b32 s73, v253, 8
	s_addc_u32 s5, s21, s5
	v_and_b32_e32 v2, 0xfc, v5
	v_lshlrev_b32_e32 v65, 2, v1
	v_lshl_add_u64 v[0:1], s[68:69], 0, v[160:161]
	s_mov_b64 s[6:7], 0x1dc6000
	s_mov_b64 s[8:9], s[72:73]
	v_readlane_b32 s72, v254, 15
	v_lshl_add_u64 v[32:33], v[0:1], 0, s[6:7]
	v_or_b32_e32 v0, 0x100, v2
	v_bfe_u32 v1, v5, 5, 3
	s_add_u32 s6, s68, 0x15c6000
	v_readlane_b32 s76, v253, 11
	v_readlane_b32 s77, v253, 12
	v_readlane_b32 s73, v254, 16
	v_or_b32_e32 v4, 0x200, v2
	v_lshlrev_b32_e32 v160, 2, v2
	v_mul_u32_u24_e32 v36, 0x4800, v1
	v_lshrrev_b32_e32 v1, 5, v0
	s_addc_u32 s7, s69, 0
	s_mov_b64 s[12:13], s[76:77]
	v_or_b32_e32 v6, 0x300, v2
	v_lshl_add_u64 v[34:35], s[4:5], 0, v[160:161]
	v_mul_u32_u24_e32 v38, 0x4800, v1
	v_lshrrev_b32_e32 v1, 5, v4
	s_and_b64 s[4:5], s[72:73], exec
	v_readlane_b32 s48, v254, 17
	v_mul_u32_u24_e32 v40, 0x4800, v1
	v_lshrrev_b32_e32 v1, 5, v6
	s_cselect_b32 s4, s12, s6
	s_cselect_b32 s6, s8, s36
	v_readlane_b32 s8, v254, 10
	s_mul_i32 s2, s48, 9
	v_mov_b32_e32 v37, v161
	v_mov_b32_e32 v39, v161
	v_mov_b32_e32 v41, v161
	v_mul_u32_u24_e32 v42, 0x4800, v1
	v_mov_b32_e32 v43, v161
	s_cselect_b32 s5, s13, s7
	s_cselect_b32 s7, s9, s37
	v_add_u32_e32 v44, s8, v3
	v_lshlrev_b32_e32 v46, 2, v2
	v_mov_b32_e32 v47, v161
	v_lshlrev_b32_e32 v48, 2, v0
	v_mov_b32_e32 v49, v161
	v_lshlrev_b32_e32 v50, 2, v4
	v_mov_b32_e32 v51, v161
	v_lshlrev_b32_e32 v52, 2, v6
	v_mov_b32_e32 v53, v161
	s_mov_b32 s10, s70
	v_readlane_b32 s74, v253, 9
	v_readlane_b32 s75, v253, 10
	v_readlane_b32 s78, v253, 13
	v_readlane_b32 s79, v253, 14
	v_readlane_b32 s80, v253, 15
	v_readlane_b32 s81, v253, 16
	v_readlane_b32 s82, v253, 17
	v_readlane_b32 s83, v253, 18
	v_readlane_b32 s49, v254, 18
	s_mov_b64 s[22:23], s[86:87]
	global_load_dwordx4 v[104:107], v[34:35], off
	global_load_dwordx4 v[108:111], v[34:35], off offset:1024
	global_load_dwordx4 v[112:115], v[34:35], off offset:2048
	global_load_dwordx4 v[116:119], v[34:35], off offset:3072
	s_branch .LBB0_116
.LBB0_115:
	s_or_b64 exec, exec, s[8:9]
	v_lshlrev_b64 v[8:9], v16, v[8:9]
	v_lshl_add_u64 v[8:9], v[18:19], 0, v[8:9]
	v_lshlrev_b64 v[10:11], 12, v[10:11]
	v_lshl_add_u64 v[8:9], v[8:9], 0, v[10:11]
	v_lshl_add_u64 v[8:9], v[8:9], 0, v[46:47]
	global_load_dwordx4 v[28:31], v[8:9], off
	global_load_dwordx4 v[20:23], v[8:9], off offset:1024
	global_load_dwordx4 v[16:19], v[8:9], off offset:2048
	s_nop 0
	global_load_dwordx4 v[8:11], v[8:9], off offset:3072
	v_add_u32_e32 v45, s2, v58
	s_waitcnt vmcnt(0) lgkmcnt(0)
	v_mov_b32_e32 v70, v25
	v_mov_b32_e32 v71, v13
	v_mov_b32_e32 v58, v24
	v_mov_b32_e32 v59, v12
	v_mov_b32_e32 v78, v5
	v_mov_b32_e32 v79, v1
	v_mul_hi_i32_i24_e32 v85, 0x3000, v45
	v_mul_i32_i24_e32 v84, 0x3000, v45
	v_pk_mul_f32 v[70:71], v[70:71], v[70:71]
	v_mov_b32_e32 v72, v26
	v_mov_b32_e32 v73, v14
	v_mov_b32_e32 v76, v4
	v_mov_b32_e32 v77, v0
	v_pk_mul_f32 v[78:79], v[78:79], v[78:79]
	v_lshl_add_u64 v[84:85], s[0:1], 0, v[84:85]
	v_pk_fma_f32 v[58:59], v[58:59], v[58:59], v[70:71]
	s_mov_b64 s[12:13], 0x1000
	v_mov_b32_e32 v74, v27
	v_mov_b32_e32 v75, v15
	v_mov_b32_e32 v80, v6
	v_mov_b32_e32 v81, v2
	v_pk_fma_f32 v[70:71], v[76:77], v[76:77], v[78:79]
	v_pk_fma_f32 v[58:59], v[72:73], v[72:73], v[58:59]
	v_lshl_add_u64 v[78:79], v[84:85], 0, s[12:13]
	v_mov_b32_e32 v82, v7
	v_mov_b32_e32 v83, v3
	v_pk_fma_f32 v[70:71], v[80:81], v[80:81], v[70:71]
	v_lshl_add_u64 v[80:81], v[84:85], 0, v[46:47]
	v_pk_fma_f32 v[58:59], v[74:75], v[74:75], v[58:59]
	v_lshl_add_u64 v[74:75], v[78:79], 0, v[46:47]
	v_mov_b64_e32 v[66:67], v[104:105]
	v_mov_b64_e32 v[68:69], v[106:107]
	v_pk_fma_f32 v[82:83], v[82:83], v[82:83], v[70:71]
	global_load_dwordx4 v[70:73], v[80:81], off
	global_load_dwordx4 v[120:123], v[80:81], off offset:1024
	global_load_dwordx4 v[124:127], v[80:81], off offset:2048
	global_load_dwordx4 v[128:131], v[80:81], off offset:3072
	s_nop 0
	global_load_dwordx4 v[132:135], v[74:75], off offset:1024
	global_load_dwordx4 v[136:139], v[74:75], off offset:2048
	global_load_dwordx4 v[140:143], v[74:75], off offset:3072
	global_load_dwordx4 v[74:77], v[74:75], off
	v_mov_b32_e32 v85, v58
	v_mov_b32_e32 v87, v82
	s_mov_b32 s8, 0x3a800000
	v_ashrrev_i32_e32 v45, 31, v44
	s_add_i32 s10, s10, s54
	s_mov_b32 s38, 0x800000
	s_cmpk_lt_i32 s10, 0x900
	v_mov_b32_e32 v94, v29
	v_mov_b32_e32 v95, v21
	v_mov_b32_e32 v92, v28
	v_mov_b32_e32 v93, v20
	v_mov_b32_e32 v102, v17
	v_mov_b32_e32 v103, v9
	v_pk_mul_f32 v[94:95], v[94:95], v[94:95]
	v_mov_b32_e32 v88, v30
	v_mov_b32_e32 v89, v22
	v_mov_b32_e32 v100, v16
	v_mov_b32_e32 v101, v8
	v_pk_mul_f32 v[102:103], v[102:103], v[102:103]
	v_pk_fma_f32 v[92:93], v[92:93], v[92:93], v[94:95]
	v_mov_b32_e32 v90, v31
	v_mov_b32_e32 v91, v23
	v_mov_b32_e32 v96, v18
	v_mov_b32_e32 v97, v10
	v_pk_fma_f32 v[94:95], v[100:101], v[100:101], v[102:103]
	v_pk_fma_f32 v[88:89], v[88:89], v[88:89], v[92:93]
	v_mov_b32_e32 v98, v19
	v_mov_b32_e32 v99, v11
	v_pk_fma_f32 v[92:93], v[96:97], v[96:97], v[94:95]
	v_pk_fma_f32 v[88:89], v[90:91], v[90:91], v[88:89]
	v_pk_fma_f32 v[90:91], v[98:99], v[98:99], v[92:93]
	v_mov_b32_e32 v84, v88
	v_mov_b32_e32 v58, v89
	v_mov_b32_e32 v86, v90
	v_pk_add_f32 v[58:59], v[84:85], v[58:59]
	v_mov_b32_e32 v82, v91
	v_pk_add_f32 v[58:59], v[58:59], v[86:87]
	v_lshl_add_u64 v[84:85], v[44:45], 0, v[36:37]
	v_pk_add_f32 v[58:59], v[58:59], v[82:83]
	ds_bpermute_b32 v83, v60, v59
	ds_bpermute_b32 v82, v60, v58
	v_lshlrev_b64 v[84:85], 6, v[84:85]
	v_lshl_add_u64 v[84:85], v[32:33], 0, v[84:85]
	s_waitcnt vmcnt(0) lgkmcnt(0)
; DI size_t kblk(int row, int col, int nrows) { return ((size_t)(col >> 5) * nrows + row) * 32 + (col & 31); }
; DI unsigned pk2(float a, float b) { hwf32x2 f = {a, b}; hwbf16x2 r = __builtin_convertvector(f, hwbf16x2); return __builtin_bit_cast(unsigned, r); }
; DI void ph_norm(const Params& p, int l, int bid, int nb) {
;     ...
;       const float rstd = rsqrtf(ss * (1.f / DM) + EPS);
; #pragma unroll
;       for (int i = 0; i < 4; ++i) {
;         const int j = (i * 64 + lane) * 4;
;         const float4 gg = *(const float4*)(g + j);
;         const float4 sh = *(const float4*)(mod[rr] + j);
;         const float4 sc = *(const float4*)(mod[rr] + 1024 + j);
;         uint2 o;
;         o.x = pk2(v[rr][i].x * rstd * gg.x * (1.f + sc.x) + sh.x, v[rr][i].y * rstd * gg.y * (1.f + sc.y) + sh.y);
;         o.y = pk2(v[rr][i].z * rstd * gg.z * (1.f + sc.z) + sh.z, v[rr][i].w * rstd * gg.w * (1.f + sc.w) + sh.w);
;         *(uint2*)(H + kblk(row, j, ROWS)) = o;
;       }
	v_pk_add_f32 v[74:75], v[74:75], 1.0 op_sel_hi:[1,0]
	v_pk_add_f32 v[58:59], v[58:59], v[82:83]
	ds_bpermute_b32 v83, v61, v59
	ds_bpermute_b32 v82, v61, v58
	v_pk_add_f32 v[76:77], v[76:77], 1.0 op_sel_hi:[1,0]
	s_waitcnt lgkmcnt(0)
	v_pk_add_f32 v[58:59], v[58:59], v[82:83]
	ds_bpermute_b32 v83, v62, v59
	ds_bpermute_b32 v82, v62, v58
	s_waitcnt lgkmcnt(0)
	v_pk_add_f32 v[58:59], v[58:59], v[82:83]
	ds_bpermute_b32 v83, v63, v59
	ds_bpermute_b32 v82, v63, v58
	s_waitcnt lgkmcnt(0)
	v_pk_add_f32 v[58:59], v[58:59], v[82:83]
	ds_bpermute_b32 v83, v64, v59
	ds_bpermute_b32 v82, v64, v58
	s_waitcnt lgkmcnt(0)
	v_pk_add_f32 v[58:59], v[58:59], v[82:83]
	ds_bpermute_b32 v83, v65, v59
	ds_bpermute_b32 v82, v65, v58
	s_waitcnt lgkmcnt(0)
	v_pk_add_f32 v[58:59], v[58:59], v[82:83]
	s_nop 0
	v_pk_fma_f32 v[58:59], v[58:59], s[8:9], v[162:163] op_sel_hi:[1,0,0]
	s_mov_b32 s8, 0x800000
	v_mul_f32_e32 v55, 0x4b800000, v59
	v_cmp_gt_f32_e32 vcc, s8, v59
	v_lshl_add_u64 v[82:83], v[78:79], 0, v[48:49]
	s_nop 0
	v_cndmask_b32_e32 v55, v59, v55, vcc
	v_rsq_f32_e32 v55, v55
	s_nop 0
	v_mul_f32_e32 v57, 0x45800000, v55
	v_cndmask_b32_e32 v86, v55, v57, vcc
	v_pk_mul_f32 v[24:25], v[24:25], v[86:87] op_sel_hi:[1,0]
	v_pk_mul_f32 v[26:27], v[26:27], v[86:87] op_sel_hi:[1,0]
	v_pk_mul_f32 v[24:25], v[66:67], v[24:25]
	v_pk_mul_f32 v[26:27], v[68:69], v[26:27]
	v_pk_fma_f32 v[24:25], v[74:75], v[24:25], v[70:71]
	v_pk_fma_f32 v[26:27], v[26:27], v[76:77], v[72:73]
	v_cvt_pk_bf16_f32 v24, v24, v25
	v_cvt_pk_bf16_f32 v25, v26, v27
	global_store_dwordx2 v[84:85], v[24:25], off
	v_mov_b64_e32 v[24:25], v[108:109]
	v_mov_b64_e32 v[26:27], v[110:111]
	s_nop 0
	v_mov_b64_e32 v[66:67], v[132:133]
	v_mov_b64_e32 v[68:69], v[134:135]
	v_mov_b64_e32 v[70:71], v[120:121]
	v_mov_b64_e32 v[72:73], v[122:123]
	v_pk_mul_f32 v[12:13], v[12:13], v[86:87] op_sel_hi:[1,0]
	v_pk_mul_f32 v[14:15], v[14:15], v[86:87] op_sel_hi:[1,0]
	v_lshl_add_u64 v[74:75], v[44:45], 0, v[38:39]
	v_lshlrev_b64 v[74:75], 6, v[74:75]
	v_lshl_add_u64 v[74:75], v[32:33], 0, v[74:75]
	v_lshl_add_u64 v[76:77], v[78:79], 0, v[50:51]
	v_pk_mul_f32 v[4:5], v[4:5], v[86:87] op_sel_hi:[1,0]
	v_pk_mul_f32 v[6:7], v[6:7], v[86:87] op_sel_hi:[1,0]
	v_pk_mul_f32 v[0:1], v[0:1], v[86:87] op_sel_hi:[1,0]
	v_pk_mul_f32 v[2:3], v[2:3], v[86:87] op_sel_hi:[1,0]
	v_add_u32_e32 v55, s2, v56
	v_mul_hi_i32_i24_e32 v57, 0x3000, v55
	v_mul_i32_i24_e32 v56, 0x3000, v55
	v_lshl_add_u64 v[56:57], s[0:1], 0, v[56:57]
	v_cmp_gt_f32_e32 vcc, s8, v58
	v_ashrrev_i32_e32 v55, 31, v54
	v_readlane_b32 s8, v254, 11
	v_pk_mul_f32 v[12:13], v[12:13], v[24:25]
	s_waitcnt lgkmcnt(0)
	v_pk_add_f32 v[24:25], v[66:67], 1.0 op_sel_hi:[1,0]
	v_pk_mul_f32 v[14:15], v[14:15], v[26:27]
	v_pk_add_f32 v[26:27], v[68:69], 1.0 op_sel_hi:[1,0]
	v_pk_fma_f32 v[12:13], v[12:13], v[24:25], v[70:71]
	v_pk_fma_f32 v[14:15], v[14:15], v[26:27], v[72:73]
	v_cvt_pk_bf16_f32 v12, v12, v13
	v_cvt_pk_bf16_f32 v13, v14, v15
	global_store_dwordx2 v[74:75], v[12:13], off
	v_mov_b64_e32 v[12:13], v[112:113]
	v_mov_b64_e32 v[14:15], v[114:115]
	s_nop 0
	v_mov_b64_e32 v[24:25], v[136:137]
	v_mov_b64_e32 v[26:27], v[138:139]
	v_mov_b64_e32 v[66:67], v[124:125]
	v_mov_b64_e32 v[68:69], v[126:127]
	v_lshl_add_u64 v[70:71], v[44:45], 0, v[40:41]
	v_lshlrev_b64 v[70:71], 6, v[70:71]
	v_lshl_add_u64 v[70:71], v[32:33], 0, v[70:71]
	v_lshl_add_u64 v[72:73], v[78:79], 0, v[52:53]
	v_pk_mul_f32 v[4:5], v[4:5], v[12:13]
	s_waitcnt lgkmcnt(0)
	v_pk_add_f32 v[12:13], v[24:25], 1.0 op_sel_hi:[1,0]
	v_pk_mul_f32 v[6:7], v[6:7], v[14:15]
	v_pk_add_f32 v[14:15], v[26:27], 1.0 op_sel_hi:[1,0]
	v_pk_fma_f32 v[4:5], v[4:5], v[12:13], v[66:67]
	v_pk_fma_f32 v[6:7], v[6:7], v[14:15], v[68:69]
	v_cvt_pk_bf16_f32 v4, v4, v5
	v_cvt_pk_bf16_f32 v5, v6, v7
	global_store_dwordx2 v[70:71], v[4:5], off
	v_mov_b64_e32 v[4:5], v[116:117]
	v_mov_b64_e32 v[6:7], v[118:119]
	s_nop 0
	v_mov_b64_e32 v[12:13], v[140:141]
	v_mov_b64_e32 v[14:15], v[142:143]
	v_mov_b64_e32 v[24:25], v[128:129]
	v_mov_b64_e32 v[26:27], v[130:131]
	v_lshl_add_u64 v[66:67], v[44:45], 0, v[42:43]
	v_lshlrev_b64 v[66:67], 6, v[66:67]
	v_lshl_add_u64 v[66:67], v[32:33], 0, v[66:67]
	v_lshl_add_u64 v[68:69], v[56:57], 0, s[12:13]
	v_lshl_add_u64 v[70:71], v[68:69], 0, v[46:47]
	v_mul_f32_e32 v45, 0x4b800000, v58
	v_cndmask_b32_e32 v45, v58, v45, vcc
	v_rsq_f32_e32 v45, v45
	v_add_u32_e32 v44, s8, v44
	v_mul_f32_e32 v58, 0x45800000, v45
	v_cndmask_b32_e32 v58, v45, v58, vcc
	v_pk_mul_f32 v[28:29], v[28:29], v[58:59] op_sel_hi:[1,0]
	v_pk_mul_f32 v[30:31], v[30:31], v[58:59] op_sel_hi:[1,0]
	v_pk_mul_f32 v[20:21], v[20:21], v[58:59] op_sel_hi:[1,0]
	v_pk_mul_f32 v[22:23], v[22:23], v[58:59] op_sel_hi:[1,0]
	v_pk_mul_f32 v[16:17], v[16:17], v[58:59] op_sel_hi:[1,0]
	v_pk_mul_f32 v[18:19], v[18:19], v[58:59] op_sel_hi:[1,0]
	v_pk_mul_f32 v[8:9], v[8:9], v[58:59] op_sel_hi:[1,0]
	v_pk_mul_f32 v[10:11], v[10:11], v[58:59] op_sel_hi:[1,0]
	v_pk_mul_f32 v[0:1], v[0:1], v[4:5]
	s_waitcnt lgkmcnt(0)
; DI size_t kblk(int row, int col, int nrows) { return ((size_t)(col >> 5) * nrows + row) * 32 + (col & 31); }
; DI unsigned pk2(float a, float b) { hwf32x2 f = {a, b}; hwbf16x2 r = __builtin_convertvector(f, hwbf16x2); return __builtin_bit_cast(unsigned, r); }
; DI void ph_norm(const Params& p, int l, int bid, int nb) {
;     ...
;       for (int i = 0; i < 4; ++i) {
;         const int j = (i * 64 + lane) * 4;
;         const float4 gg = *(const float4*)(g + j);
;         const float4 sh = *(const float4*)(mod[rr] + j);
;         const float4 sc = *(const float4*)(mod[rr] + 1024 + j);
;         uint2 o;
;         o.x = pk2(v[rr][i].x * rstd * gg.x * (1.f + sc.x) + sh.x, v[rr][i].y * rstd * gg.y * (1.f + sc.y) + sh.y);
;         o.y = pk2(v[rr][i].z * rstd * gg.z * (1.f + sc.z) + sh.z, v[rr][i].w * rstd * gg.w * (1.f + sc.w) + sh.w);
;         *(uint2*)(H + kblk(row, j, ROWS)) = o;
;       }
	v_pk_add_f32 v[4:5], v[12:13], 1.0 op_sel_hi:[1,0]
	v_pk_mul_f32 v[2:3], v[2:3], v[6:7]
	v_pk_add_f32 v[6:7], v[14:15], 1.0 op_sel_hi:[1,0]
	v_pk_fma_f32 v[0:1], v[0:1], v[4:5], v[24:25]
	v_pk_fma_f32 v[2:3], v[2:3], v[6:7], v[26:27]
	v_cvt_pk_bf16_f32 v0, v0, v1
	v_cvt_pk_bf16_f32 v1, v2, v3
	global_store_dwordx2 v[66:67], v[0:1], off
	v_mov_b64_e32 v[0:1], v[104:105]
	v_mov_b64_e32 v[2:3], v[106:107]
	s_nop 0
	global_load_dwordx4 v[4:7], v[70:71], off
	global_load_dwordx4 v[144:147], v[70:71], off offset:1024
	global_load_dwordx4 v[148:151], v[70:71], off offset:2048
	global_load_dwordx4 v[152:155], v[70:71], off offset:3072
	v_lshl_add_u64 v[24:25], v[56:57], 0, v[46:47]
	global_load_dwordx4 v[12:15], v[24:25], off
	global_load_dwordx4 v[156:159], v[24:25], off offset:1024
	global_load_dwordx4 v[196:199], v[24:25], off offset:2048
	global_load_dwordx4 v[200:203], v[24:25], off offset:3072
	v_lshl_add_u64 v[26:27], v[54:55], 0, v[36:37]
	v_lshlrev_b64 v[26:27], 6, v[26:27]
	v_lshl_add_u64 v[26:27], v[32:33], 0, v[26:27]
	v_lshl_add_u64 v[56:57], v[68:69], 0, v[48:49]
	s_waitcnt vmcnt(0)
	v_pk_mul_f32 v[0:1], v[0:1], v[28:29]
	s_waitcnt lgkmcnt(0)
	v_pk_add_f32 v[4:5], v[4:5], 1.0 op_sel_hi:[1,0]
	v_pk_mul_f32 v[2:3], v[2:3], v[30:31]
	v_pk_add_f32 v[6:7], v[6:7], 1.0 op_sel_hi:[1,0]
	v_pk_fma_f32 v[0:1], v[4:5], v[0:1], v[12:13]
	v_pk_fma_f32 v[2:3], v[2:3], v[6:7], v[14:15]
	v_cvt_pk_bf16_f32 v0, v0, v1
	v_cvt_pk_bf16_f32 v1, v2, v3
	global_store_dwordx2 v[26:27], v[0:1], off
	v_mov_b64_e32 v[0:1], v[108:109]
	v_mov_b64_e32 v[2:3], v[110:111]
	s_nop 0
	v_mov_b64_e32 v[4:5], v[144:145]
	v_mov_b64_e32 v[6:7], v[146:147]
	v_mov_b64_e32 v[12:13], v[156:157]
	v_mov_b64_e32 v[14:15], v[158:159]
	v_lshl_add_u64 v[26:27], v[54:55], 0, v[38:39]
	v_lshlrev_b64 v[26:27], 6, v[26:27]
	v_lshl_add_u64 v[26:27], v[32:33], 0, v[26:27]
	v_lshl_add_u64 v[28:29], v[68:69], 0, v[50:51]
	v_pk_mul_f32 v[0:1], v[20:21], v[0:1]
	s_waitcnt lgkmcnt(0)
	v_pk_add_f32 v[4:5], v[4:5], 1.0 op_sel_hi:[1,0]
	v_pk_mul_f32 v[2:3], v[22:23], v[2:3]
	v_pk_add_f32 v[6:7], v[6:7], 1.0 op_sel_hi:[1,0]
	v_pk_fma_f32 v[0:1], v[0:1], v[4:5], v[12:13]
	v_pk_fma_f32 v[2:3], v[2:3], v[6:7], v[14:15]
	v_cvt_pk_bf16_f32 v0, v0, v1
	v_cvt_pk_bf16_f32 v1, v2, v3
	global_store_dwordx2 v[26:27], v[0:1], off
	v_mov_b64_e32 v[0:1], v[112:113]
	v_mov_b64_e32 v[2:3], v[114:115]
	s_nop 0
	v_mov_b64_e32 v[4:5], v[148:149]
	v_mov_b64_e32 v[6:7], v[150:151]
	v_mov_b64_e32 v[12:13], v[196:197]
	v_mov_b64_e32 v[14:15], v[198:199]
	v_lshl_add_u64 v[20:21], v[54:55], 0, v[40:41]
	v_lshlrev_b64 v[20:21], 6, v[20:21]
	v_lshl_add_u64 v[20:21], v[32:33], 0, v[20:21]
	v_lshl_add_u64 v[22:23], v[68:69], 0, v[52:53]
	v_pk_mul_f32 v[0:1], v[16:17], v[0:1]
	s_waitcnt lgkmcnt(0)
	v_pk_add_f32 v[4:5], v[4:5], 1.0 op_sel_hi:[1,0]
	v_pk_mul_f32 v[2:3], v[18:19], v[2:3]
	v_pk_add_f32 v[6:7], v[6:7], 1.0 op_sel_hi:[1,0]
	v_pk_fma_f32 v[0:1], v[0:1], v[4:5], v[12:13]
	v_pk_fma_f32 v[2:3], v[2:3], v[6:7], v[14:15]
	v_cvt_pk_bf16_f32 v0, v0, v1
	v_cvt_pk_bf16_f32 v1, v2, v3
	global_store_dwordx2 v[20:21], v[0:1], off
	v_mov_b64_e32 v[0:1], v[116:117]
	v_mov_b64_e32 v[2:3], v[118:119]
	s_nop 0
	v_mov_b64_e32 v[4:5], v[152:153]
	v_mov_b64_e32 v[6:7], v[154:155]
	v_mov_b64_e32 v[12:13], v[200:201]
	v_mov_b64_e32 v[14:15], v[202:203]
	v_lshl_add_u64 v[16:17], v[54:55], 0, v[42:43]
	v_lshlrev_b64 v[16:17], 6, v[16:17]
	v_lshl_add_u64 v[16:17], v[32:33], 0, v[16:17]
	v_pk_mul_f32 v[0:1], v[8:9], v[0:1]
	s_waitcnt lgkmcnt(0)
	v_pk_add_f32 v[4:5], v[4:5], 1.0 op_sel_hi:[1,0]
	v_pk_mul_f32 v[2:3], v[10:11], v[2:3]
	v_pk_add_f32 v[6:7], v[6:7], 1.0 op_sel_hi:[1,0]
	v_pk_fma_f32 v[0:1], v[0:1], v[4:5], v[12:13]
	v_pk_fma_f32 v[2:3], v[2:3], v[6:7], v[14:15]
	v_cvt_pk_bf16_f32 v0, v0, v1
	v_cvt_pk_bf16_f32 v1, v2, v3
	global_store_dwordx2 v[16:17], v[0:1], off
	s_cbranch_scc0 .LBB0_124
